# attention epilogue: counted wait vmcnt(20) so next-unit staging streams under the epilogue (on top of v20)
# baseline (speedup 1.0000x reference)
; #define LAS __attribute__((address_space(3)))
;     __device__ __forceinline__ int lane_() const { return hw_lane(); }
; __device__ __forceinline__ void attn_stage(Frame& F, const Ptrs& P, int u, bf16x8 (&qa)[4]) {
;     int lane = F.lane_(); asm volatile("" : "+v"(lane));
;     const int b = u >> 8, nb = u & 63, kvh = (u >> 6) & 3;
;     const int wid = F.wave, r32 = lane & 31, hi = lane >> 5;
;     LAS unsigned char* lds = F.lds;
;     const int hq = kvh * 4 + (wid >> 1), r0 = 64 * (wid & 1);
;     const size_t qrow = (size_t)b * SEQ + nb * 128 + r0;
;     const bf16* Qw = (const bf16*)(P.ws + WS_YG) + (qrow + r32) * 2048 + 1024 + hq * 64;
; #pragma unroll
;     for (int d0 = 0; d0 < 4; ++d0) qa[d0] = *(const bf16x8*)(Qw + d0 * 16 + hi * 8);
; #pragma unroll
;     for (int d0 = 0; d0 < 4; ++d0) __builtin_amdgcn_global_load_lds((const unsigned*)(Qw + (size_t)32 * 2048 + d0 * 16 + hi * 8), (LAS unsigned*)(lds + LDS_QB + wid * 4096 + d0 * 1024), 16, 0, 0);
;     const int t0 = nb * 128 - 128;
;     const bf16* Kh = (const bf16*)(P.ws + WS_K) + (size_t)b * SEQ * 256 + kvh * 64; const bf16* Vh = (const bf16*)(P.ws + WS_V) + (size_t)b * SEQ * 256 + kvh * 64;
; #pragma unroll
;     for (int j = 0; j < 6; ++j) {
;         int tk = t0 + j * 64 + lane; tk = tk < 0 ? 0 : (tk > SEQ - 1 ? SEQ - 1 : tk);
;         __builtin_amdgcn_global_load_lds((const unsigned*)(Kh + (size_t)tk * 256 + wid * 8), (LAS unsigned*)(lds + LDS_K + j * 8192 + wid * 1024), 16, 0, 0);
;         int tv = t0 + j * 64 + 16 * (wid & 3) + (lane >> 2); tv = tv < 0 ? 0 : (tv > SEQ - 1 ? SEQ - 1 : tv);
;         __builtin_amdgcn_global_load_lds((const unsigned*)(Vh + (size_t)tv * 256 + (wid >> 2) * 32 + (lane & 3) * 8), (LAS unsigned*)(lds + LDS_V + j * 8192 + wid * 1024), 16, 0, 0);
;     }
; __device__ __forceinline__ void attn_unit(Frame& F, const Ptrs& P, int u, int u_next, bf16x8 (&qa)[4], ScanRider& R) {
;     ...
;     __builtin_amdgcn_s_setprio(0);
;     u32x4 gva[4], gvb[4];
;     { const bf16* gp = Gb + (qrow + r32) * 1024 + hq * 64 + 8 * hi;
; #pragma unroll
;       for (int k = 0; k < 4; ++k) { gva[k] = *(const u32x4*)(gp + 16 * k); gvb[k] = *(const u32x4*)(gp + (size_t)32 * 1024 + 16 * k); } }
;     __syncthreads();
;     if (u_next >= 0) attn_stage(F, P, u_next, qa);
.LBB0_670:
	s_ashr_i32 s4, s6, 8
	s_ashr_i32 s5, s4, 31
	s_lshl_b64 s[4:5], s[4:5], 13
	s_lshl_b32 s28, s81, 7
	s_or_b32 s4, s4, s28
	s_add_i32 s80, s6, 0x100
	s_or_b64 s[28:29], s[4:5], s[14:15]
	s_lshl_b32 s81, s79, 6
	s_cmpk_gt_i32 s6, 0xff
	s_cselect_b64 s[4:5], -1, 0
	s_cmpk_lt_i32 s6, 0x100
	v_or_b32_e32 v100, s28, v177
	v_mov_b32_e32 v101, s29
	s_cselect_b32 s82, s80, -1
	s_setprio 0
	v_lshlrev_b64 v[2:3], 11, v[100:101]
	v_lshl_add_u64 v[2:3], s[20:21], 0, v[2:3]
	s_lshl_b32 s6, s79, 7
	v_lshlrev_b32_e32 v14, 3, v14
	v_lshl_add_u64 v[2:3], v[2:3], 0, s[6:7]
	v_ashrrev_i32_e32 v15, 31, v14
	v_lshl_add_u64 v[2:3], v[14:15], 1, v[2:3]
	s_mov_b32 s6, 0x10000
	v_add_co_u32_e32 v4, vcc, s6, v2
	s_cmp_gt_i32 s82, -1
	s_nop 0
	v_addc_co_u32_e32 v5, vcc, 0, v3, vcc
	global_load_dwordx4 v[96:99], v[2:3], off
	global_load_dwordx4 v[92:95], v[2:3], off offset:32
	global_load_dwordx4 v[80:83], v[4:5], off
	global_load_dwordx4 v[10:13], v[4:5], off offset:32
	global_load_dwordx4 v[88:91], v[2:3], off offset:64
	global_load_dwordx4 v[84:87], v[2:3], off offset:96
	global_load_dwordx4 v[6:9], v[4:5], off offset:64
	s_nop 0
	global_load_dwordx4 v[2:5], v[4:5], off offset:96
	s_barrier
	s_cbranch_scc0 .LBB0_672
	v_mbcnt_lo_u32_b32 v108, -1, 0
	v_mbcnt_hi_u32_b32 v108, -1, v108
	s_lshr_b32 s6, s82, 8
	s_bfe_u32 s84, s82, 0x20006
	s_lshl_b32 s82, s82, 7
	s_and_b32 s86, s82, 0x1f80
	v_and_or_b32 v0, v108, 31, s12
	s_lshl_b64 s[82:83], s[6:7], 25
	v_or_b32_e32 v0, s86, v0
	s_add_u32 s82, s96, s82
	v_lshlrev_b32_e32 v0, 12, v0
	s_addc_u32 s83, s97, s83
	v_lshl_add_u64 v[102:103], s[82:83], 0, v[0:1]
	s_lshl_b32 s82, s84, 8
	s_add_i32 s82, s82, s13
	v_ashrrev_i32_e32 v0, 2, v108
	s_ashr_i32 s83, s82, 31
	v_and_b32_e32 v104, -8, v0
	v_lshl_add_u64 v[102:103], s[82:83], 1, v[102:103]
	v_ashrrev_i32_e32 v105, 31, v104
	v_lshl_add_u64 v[102:103], v[104:105], 1, v[102:103]
	v_lshl_add_u64 v[104:105], v[102:103], 0, s[22:23]
	v_add_co_u32_e32 v106, vcc, s73, v102
	s_mov_b64 s[82:83], 0x8c20800
	s_mov_b32 m0, s30
	v_addc_co_u32_e32 v107, vcc, 0, v103, vcc
	global_load_dwordx4 v[144:147], v[104:105], off offset:32
	global_load_dwordx4 v[148:151], v[104:105], off offset:64
	global_load_dwordx4 v[152:155], v[106:107], off offset:2048
	global_load_dwordx4 v[156:159], v[104:105], off offset:96
	v_lshl_add_u64 v[104:105], v[102:103], 0, s[82:83]
	s_mov_b64 s[82:83], 0x8c20820
	global_load_lds_dwordx4 v[104:105], off
	v_lshl_add_u64 v[104:105], v[102:103], 0, s[82:83]
	s_mov_b32 m0, s74
	s_mov_b64 s[82:83], 0x8c20840
	global_load_lds_dwordx4 v[104:105], off
	v_lshl_add_u64 v[104:105], v[102:103], 0, s[82:83]
	s_mov_b64 s[82:83], 0x8c20860
	v_lshl_add_u64 v[102:103], v[102:103], 0, s[82:83]
	s_add_i32 s87, s86, 0xffffff80
	s_lshl_b64 s[82:83], s[6:7], 22
	s_add_u32 s6, s31, s82
	s_addc_u32 s85, s33, s83
	s_lshl_b32 s84, s84, 7
	s_add_u32 s6, s6, s84
	s_addc_u32 s85, s85, 0
	s_add_u32 s82, s34, s82
	s_addc_u32 s83, s35, s83
	s_add_u32 s84, s82, s84
	s_addc_u32 s88, s83, 0
	s_add_u32 s82, s6, s77
	s_addc_u32 s83, s85, 0
	s_mov_b32 m0, s75
	v_add_u32_e32 v106, s62, v0
	s_add_u32 s84, s84, s63
	v_lshlrev_b32_e32 v0, 4, v108
	global_load_lds_dwordx4 v[104:105], off
	s_mov_b32 m0, s76
	s_addc_u32 s85, s88, 0
	v_and_b32_e32 v0, 48, v0
	global_load_lds_dwordx4 v[102:103], off
	v_lshl_add_u64 v[102:103], s[84:85], 0, v[0:1]
	v_add_u32_e32 v0, s87, v108
	v_med3_i32 v0, v0, 0, v169
	v_lshlrev_b32_e32 v0, 9, v0
	s_mov_b32 m0, s61
	s_sub_i32 s6, s86, 64
	global_load_lds_dwordx4 v0, s[82:83]
	v_add_u32_e32 v0, s87, v106
	v_med3_i32 v0, v0, 0, v169
	v_lshlrev_b32_e32 v0, 9, v0
	v_lshl_add_u64 v[104:105], v[102:103], 0, v[0:1]
	v_add_u32_e32 v0, s6, v108
	s_mov_b32 m0, s64
	v_med3_i32 v0, v0, 0, v169
	global_load_lds_dwordx4 v[104:105], off
	v_lshlrev_b32_e32 v0, 9, v0
	s_mov_b32 m0, s65
	s_nop 0
	global_load_lds_dwordx4 v0, s[82:83]
	v_add_u32_e32 v0, s6, v106
	v_med3_i32 v0, v0, 0, v169
	v_lshlrev_b32_e32 v0, 9, v0
	v_lshl_add_u64 v[104:105], v[102:103], 0, v[0:1]
	v_add_u32_e32 v0, s86, v108
	s_mov_b32 m0, s68
	v_med3_i32 v0, v0, 0, v169
	global_load_lds_dwordx4 v[104:105], off
	v_lshlrev_b32_e32 v0, 9, v0
	s_mov_b32 m0, s69
	s_or_b32 s6, s86, 64
	global_load_lds_dwordx4 v0, s[82:83]
	v_add_u32_e32 v0, s86, v106
	v_med3_i32 v0, v0, 0, v169
	v_lshlrev_b32_e32 v0, 9, v0
	v_lshl_add_u64 v[104:105], v[102:103], 0, v[0:1]
	v_add_u32_e32 v0, s6, v108
	s_add_i32 m0, s64, 0x4000
	v_med3_i32 v0, v0, 0, v169
	global_load_lds_dwordx4 v[104:105], off
	v_lshlrev_b32_e32 v0, 9, v0
	s_mov_b32 m0, s70
	s_nop 0
	global_load_lds_dwordx4 v0, s[82:83]
	v_add_u32_e32 v0, s6, v106
	v_med3_i32 v0, v0, 0, v169
	v_lshlrev_b32_e32 v0, 9, v0
	s_add_i32 s6, s86, 0x80
	v_lshl_add_u64 v[104:105], v[102:103], 0, v[0:1]
	v_add_u32_e32 v0, s6, v108
	s_add_i32 m0, s64, 0x6000
	v_med3_i32 v0, v0, 0, v169
	global_load_lds_dwordx4 v[104:105], off
	v_lshlrev_b32_e32 v0, 9, v0
	s_mov_b32 m0, s71
	s_addk_i32 s86, 0xc0
	global_load_lds_dwordx4 v0, s[82:83]
	v_add_u32_e32 v0, s6, v106
	v_med3_i32 v0, v0, 0, v169
	v_lshlrev_b32_e32 v0, 9, v0
	v_lshl_add_u64 v[104:105], v[102:103], 0, v[0:1]
	v_add_u32_e32 v0, s86, v108
	s_add_i32 m0, s64, 0x8000
	v_med3_i32 v0, v0, 0, v169
	global_load_lds_dwordx4 v[104:105], off
	v_lshlrev_b32_e32 v0, 9, v0
	s_mov_b32 m0, s72
	s_nop 0
	global_load_lds_dwordx4 v0, s[82:83]
	v_add_u32_e32 v0, s86, v106
	v_med3_i32 v0, v0, 0, v169
	v_lshlrev_b32_e32 v0, 9, v0
	v_lshl_add_u64 v[102:103], v[102:103], 0, v[0:1]
	s_add_i32 m0, s64, 0xa000
	s_nop 0
	global_load_lds_dwordx4 v[102:103], off
	v_lshlrev_b64 v[100:101], 12, v[100:101]
	v_lshl_add_u64 v[100:101], s[96:97], 0, v[100:101]
	s_lshl_b32 s6, s81, 1
	v_lshl_add_u64 v[100:101], v[100:101], 0, s[6:7]
	s_waitcnt vmcnt(20)
	s_branch .Lattn_ep_go

; __device__ __forceinline__ unsigned cvtpk(float lo, float hi) { f32x2_t v = {lo, hi}; bf16x2_t b = __builtin_convertvector(v, bf16x2_t); return __builtin_bit_cast(unsigned, b); }
; __device__ __forceinline__ float lo16(unsigned u) { return __uint_as_float(u << 16); }
; __device__ __forceinline__ void attn_unit(Frame& F, const Ptrs& P, int u, int u_next, bf16x8 (&qa)[4], ScanRider& R) {
;     ...
;     u32x2 gA[8], gB[8];
; #pragma unroll
;     for (int k = 0; k < 4; ++k) {
;         const u32x4 va = gva[k], vb = gvb[k];
;         auto r0 = __builtin_amdgcn_permlane32_swap(va.x, va.z, false, false); auto r1 = __builtin_amdgcn_permlane32_swap(va.y, va.w, false, false);
;         gA[2 * k].x = r0[0]; gA[2 * k + 1].x = r0[1]; gA[2 * k].y = r1[0]; gA[2 * k + 1].y = r1[1];
;         auto r2 = __builtin_amdgcn_permlane32_swap(vb.x, vb.z, false, false); auto r3 = __builtin_amdgcn_permlane32_swap(vb.y, vb.w, false, false);
;         gB[2 * k].x = r2[0]; gB[2 * k + 1].x = r2[1]; gB[2 * k].y = r3[0]; gB[2 * k + 1].y = r3[1]; }
; #pragma unroll
;     for (int s2 = 0; s2 < 2; ++s2) {
;         float l = s2 ? lB : lA;
;         { auto rr = __builtin_amdgcn_permlane32_swap(__float_as_uint(l), __float_as_uint(l), false, false); l = __uint_as_float(rr[0]) + __uint_as_float(rr[1]); }
;         const float il = __builtin_amdgcn_rcpf(l); float ss = 0.f;
;         bf16* op = Qw + (size_t)(32 * s2) * 2048 + 8 * hi;
; #pragma unroll
;         for (int d0 = 0; d0 < 2; ++d0)
; #pragma unroll
;             for (int kk = 0; kk < 2; ++kk) { u32x2 w[2];
; #pragma unroll
;                 for (int e = 0; e < 2; ++e) { const int g4 = 2 * kk + e; const u32x2 gv = s2 ? gB[d0 * 4 + g4] : gA[d0 * 4 + g4]; const f32x16& o = s2 ? oB[d0] : oA[d0];
;                     const float y0 = o[4 * g4] * il * lo16(gv.x), y1 = o[4 * g4 + 1] * il * hi16(gv.x), y2 = o[4 * g4 + 2] * il * lo16(gv.y), y3 = o[4 * g4 + 3] * il * hi16(gv.y);
;                     ss += (y0 * y0 + y1 * y1) + (y2 * y2 + y3 * y3);
;                     w[e].x = cvtpk(y0, y1); w[e].y = cvtpk(y2, y3); }
;                 auto r0 = __builtin_amdgcn_permlane32_swap(w[0].x, w[1].x, false, false); auto r1 = __builtin_amdgcn_permlane32_swap(w[0].y, w[1].y, false, false);
;                 if (!dry) *(u32x4*)(op + 32 * d0 + 16 * kk) = (u32x4){r0[0], r1[0], r0[1], r1[1]}; }
.Lattn_ep_go:
	v_mov_b32_e32 v102, v98
	v_mov_b32_e32 v98, v83
	v_mov_b32_e32 v83, v4
	v_mov_b32_e32 v4, v181
	s_nop 1
	v_permlane32_swap_b32_e32 v181, v4
	v_add_f32_e32 v4, v181, v4
	v_mov_b32_e32 v108, v86
	v_mov_b32_e32 v109, v87
	v_lshl_add_u64 v[86:87], v[14:15], 1, v[100:101]
	s_lshl_b64 s[28:29], s[28:29], 2
	v_rcp_f32_e32 v100, v4
	s_add_u32 s81, s50, s28
	s_addc_u32 s82, s51, s29
	s_add_i32 s6, s79, 16
	v_permlane32_swap_b32_e32 v96, v102
	v_mov_b32_e32 v103, v99
	s_lshl_b64 s[28:29], s[6:7], 16
	s_nop 0
	v_permlane32_swap_b32_e32 v97, v103
	v_mov_b32_e32 v104, v94
	v_mov_b32_e32 v105, v95
	v_mov_b32_e32 v95, v12
	v_mov_b32_e32 v94, v13
	s_add_u32 s28, s81, s28
	v_lshlrev_b32_e32 v12, 16, v96
	v_and_b32_e32 v13, 0xffff0000, v96
	v_pk_mul_f32 v[14:15], v[64:65], v[100:101] op_sel_hi:[1,0]
	s_addc_u32 s29, s82, s29
	v_lshlrev_b32_e32 v0, 2, v177
	v_pk_mul_f32 v[12:13], v[14:15], v[12:13]
	v_lshlrev_b32_e32 v14, 16, v97
	v_and_b32_e32 v15, 0xffff0000, v97
	v_pk_mul_f32 v[64:65], v[66:67], v[100:101] op_sel_hi:[1,0]
	v_mov_b32_e32 v99, v82
	v_mov_b32_e32 v82, v5
	v_lshl_add_u64 v[4:5], s[28:29], 0, v[0:1]
	v_pk_mul_f32 v[14:15], v[64:65], v[14:15]
	v_mul_f32_e32 v0, v13, v13
	v_pk_fma_f32 v[64:65], v[12:13], v[12:13], v[0:1] op_sel_hi:[1,1,0]
	v_mul_f32_e32 v0, v15, v15
	v_pk_fma_f32 v[66:67], v[14:15], v[14:15], v[0:1] op_sel_hi:[1,1,0]
	v_cvt_pk_bf16_f32 v12, v12, v13
	v_pk_add_f32 v[64:65], v[64:65], v[66:67]
	v_cvt_pk_bf16_f32 v13, v14, v15
	v_lshlrev_b32_e32 v14, 16, v102
	v_and_b32_e32 v15, 0xffff0000, v102
	v_pk_mul_f32 v[66:67], v[68:69], v[100:101] op_sel_hi:[1,0]
	v_pk_mul_f32 v[68:69], v[70:71], v[100:101] op_sel_hi:[1,0]
	v_pk_mul_f32 v[14:15], v[66:67], v[14:15]
	v_lshlrev_b32_e32 v66, 16, v103
	v_and_b32_e32 v67, 0xffff0000, v103
	v_pk_mul_f32 v[66:67], v[68:69], v[66:67]
	v_mul_f32_e32 v0, v15, v15
	v_pk_fma_f32 v[68:69], v[14:15], v[14:15], v[0:1] op_sel_hi:[1,1,0]
	v_mul_f32_e32 v0, v67, v67
	v_pk_fma_f32 v[70:71], v[66:67], v[66:67], v[0:1] op_sel_hi:[1,1,0]
	v_cvt_pk_bf16_f32 v14, v14, v15
	v_cvt_pk_bf16_f32 v15, v66, v67
	v_add_co_u32_e32 v66, vcc, s73, v86
	v_permlane32_swap_b32_e32 v92, v104
	v_permlane32_swap_b32_e32 v12, v14
	v_permlane32_swap_b32_e32 v13, v15
	v_addc_co_u32_e32 v67, vcc, 0, v87, vcc
	v_permlane32_swap_b32_e32 v93, v105
	global_store_dwordx4 v[66:67], v[12:15], off offset:2048
	v_pk_mul_f32 v[66:67], v[74:75], v[100:101] op_sel_hi:[1,0]
	v_pk_add_f32 v[68:69], v[68:69], v[70:71]
	v_lshlrev_b32_e32 v12, 16, v92
	v_and_b32_e32 v13, 0xffff0000, v92
	v_pk_mul_f32 v[14:15], v[72:73], v[100:101] op_sel_hi:[1,0]
	v_pk_add_f32 v[64:65], v[64:65], v[68:69]
	v_pk_mul_f32 v[12:13], v[14:15], v[12:13]
	v_lshlrev_b32_e32 v14, 16, v93
	v_and_b32_e32 v15, 0xffff0000, v93
	v_pk_mul_f32 v[14:15], v[66:67], v[14:15]
	v_mul_f32_e32 v0, v13, v13
	v_pk_fma_f32 v[66:67], v[12:13], v[12:13], v[0:1] op_sel_hi:[1,1,0]
	v_mul_f32_e32 v0, v15, v15
	v_pk_fma_f32 v[68:69], v[14:15], v[14:15], v[0:1] op_sel_hi:[1,1,0]
	v_cvt_pk_bf16_f32 v12, v12, v13
	v_pk_add_f32 v[66:67], v[66:67], v[68:69]
	v_cvt_pk_bf16_f32 v13, v14, v15
	v_pk_add_f32 v[64:65], v[66:67], v[64:65]
	v_lshlrev_b32_e32 v14, 16, v104
	v_and_b32_e32 v15, 0xffff0000, v104
	v_pk_mul_f32 v[66:67], v[76:77], v[100:101] op_sel_hi:[1,0]
	v_pk_mul_f32 v[68:69], v[78:79], v[100:101] op_sel_hi:[1,0]
	v_pk_mul_f32 v[14:15], v[66:67], v[14:15]
	v_lshlrev_b32_e32 v66, 16, v105
	v_and_b32_e32 v67, 0xffff0000, v105
	v_pk_mul_f32 v[66:67], v[68:69], v[66:67]
	v_mul_f32_e32 v0, v15, v15
	v_mov_b32_e32 v106, v90
	v_pk_fma_f32 v[68:69], v[14:15], v[14:15], v[0:1] op_sel_hi:[1,1,0]
	v_cvt_pk_bf16_f32 v14, v14, v15
	v_cvt_pk_bf16_f32 v15, v66, v67
	v_permlane32_swap_b32_e32 v88, v106
	v_mov_b32_e32 v107, v91
	v_mov_b32_e32 v91, v8
	v_mov_b32_e32 v90, v9
	v_lshl_add_u64 v[8:9], v[86:87], 0, s[22:23]
	v_permlane32_swap_b32_e32 v12, v14
; __device__ __forceinline__ unsigned cvtpk(float lo, float hi) { f32x2_t v = {lo, hi}; bf16x2_t b = __builtin_convertvector(v, bf16x2_t); return __builtin_bit_cast(unsigned, b); }
; __device__ __forceinline__ float lo16(unsigned u) { return __uint_as_float(u << 16); }
; __device__ __forceinline__ float hi16(unsigned u) { return __uint_as_float(u & 0xffff0000u); }
; __device__ __forceinline__ unsigned cvtpk(float lo, float hi) { f32x2_t v = {lo, hi}; bf16x2_t b = __builtin_convertvector(v, bf16x2_t); return __builtin_bit_cast(unsigned, b); }
; __device__ __forceinline__ float lo16(unsigned u) { return __uint_as_float(u << 16); }
; __device__ __forceinline__ float hi16(unsigned u) { return __uint_as_float(u & 0xffff0000u); }
; __device__ __forceinline__ void attn_unit(Frame& F, const Ptrs& P, int u, int u_next, bf16x8 (&qa)[4], ScanRider& R) {
;     ...
;         for (int d0 = 0; d0 < 2; ++d0)
; #pragma unroll
;             for (int kk = 0; kk < 2; ++kk) { u32x2 w[2];
; #pragma unroll
;                 for (int e = 0; e < 2; ++e) { const int g4 = 2 * kk + e; const u32x2 gv = s2 ? gB[d0 * 4 + g4] : gA[d0 * 4 + g4]; const f32x16& o = s2 ? oB[d0] : oA[d0];
;                     const float y0 = o[4 * g4] * il * lo16(gv.x), y1 = o[4 * g4 + 1] * il * hi16(gv.x), y2 = o[4 * g4 + 2] * il * lo16(gv.y), y3 = o[4 * g4 + 3] * il * hi16(gv.y);
;                     ss += (y0 * y0 + y1 * y1) + (y2 * y2 + y3 * y3);
;                     w[e].x = cvtpk(y0, y1); w[e].y = cvtpk(y2, y3); }
;                 auto r0 = __builtin_amdgcn_permlane32_swap(w[0].x, w[1].x, false, false); auto r1 = __builtin_amdgcn_permlane32_swap(w[0].y, w[1].y, false, false);
;                 if (!dry) *(u32x4*)(op + 32 * d0 + 16 * kk) = (u32x4){r0[0], r1[0], r0[1], r1[1]}; }
;         { auto rr = __builtin_amdgcn_permlane32_swap(__float_as_uint(ss), __float_as_uint(ss), false, false); ss = __uint_as_float(rr[0]) + __uint_as_float(rr[1]); }
;         if (!dry && hi == 0) SSQ[(size_t)(16 + hq) * M + qrow + 32 * s2 + r32] = ss;
	v_permlane32_swap_b32_e32 v13, v15
	v_permlane32_swap_b32_e32 v89, v107
	global_store_dwordx4 v[8:9], v[12:15], off offset:32
	v_mul_f32_e32 v0, v67, v67
	v_pk_fma_f32 v[70:71], v[66:67], v[66:67], v[0:1] op_sel_hi:[1,1,0]
	v_lshlrev_b32_e32 v12, 16, v88
	v_and_b32_e32 v13, 0xffff0000, v88
	v_pk_mul_f32 v[14:15], v[48:49], v[100:101] op_sel_hi:[1,0]
	v_pk_mul_f32 v[48:49], v[50:51], v[100:101] op_sel_hi:[1,0]
	v_pk_mul_f32 v[12:13], v[14:15], v[12:13]
	v_lshlrev_b32_e32 v14, 16, v89
	v_and_b32_e32 v15, 0xffff0000, v89
	v_pk_mul_f32 v[14:15], v[48:49], v[14:15]
	v_mul_f32_e32 v0, v13, v13
	v_pk_fma_f32 v[48:49], v[12:13], v[12:13], v[0:1] op_sel_hi:[1,1,0]
	v_mul_f32_e32 v0, v15, v15
	v_pk_fma_f32 v[50:51], v[14:15], v[14:15], v[0:1] op_sel_hi:[1,1,0]
	v_cvt_pk_bf16_f32 v12, v12, v13
	v_pk_add_f32 v[48:49], v[48:49], v[50:51]
	v_cvt_pk_bf16_f32 v13, v14, v15
	v_lshlrev_b32_e32 v14, 16, v106
	v_and_b32_e32 v15, 0xffff0000, v106
	v_pk_mul_f32 v[50:51], v[52:53], v[100:101] op_sel_hi:[1,0]
	v_pk_mul_f32 v[52:53], v[54:55], v[100:101] op_sel_hi:[1,0]
	v_pk_mul_f32 v[14:15], v[50:51], v[14:15]
	v_lshlrev_b32_e32 v50, 16, v107
	v_and_b32_e32 v51, 0xffff0000, v107
	v_pk_mul_f32 v[50:51], v[52:53], v[50:51]
	v_mul_f32_e32 v0, v15, v15
	v_pk_fma_f32 v[52:53], v[14:15], v[14:15], v[0:1] op_sel_hi:[1,1,0]
	v_cvt_pk_bf16_f32 v14, v14, v15
	v_cvt_pk_bf16_f32 v15, v50, v51
	v_permlane32_swap_b32_e32 v84, v108
	v_permlane32_swap_b32_e32 v12, v14
	v_permlane32_swap_b32_e32 v13, v15
	v_permlane32_swap_b32_e32 v85, v109
	v_mul_f32_e32 v0, v51, v51
	global_store_dwordx4 v[8:9], v[12:15], off offset:64
	v_pk_add_f32 v[68:69], v[68:69], v[70:71]
	v_pk_fma_f32 v[54:55], v[50:51], v[50:51], v[0:1] op_sel_hi:[1,1,0]
	v_lshlrev_b32_e32 v12, 16, v84
	v_and_b32_e32 v13, 0xffff0000, v84
	v_pk_mul_f32 v[14:15], v[56:57], v[100:101] op_sel_hi:[1,0]
	v_pk_mul_f32 v[50:51], v[58:59], v[100:101] op_sel_hi:[1,0]
	v_pk_mul_f32 v[12:13], v[14:15], v[12:13]
	v_lshlrev_b32_e32 v14, 16, v85
	v_and_b32_e32 v15, 0xffff0000, v85
	v_pk_add_f32 v[64:65], v[68:69], v[64:65]
	v_pk_mul_f32 v[14:15], v[50:51], v[14:15]
	v_mul_f32_e32 v0, v13, v13
	v_pk_add_f32 v[48:49], v[48:49], v[64:65]
	v_pk_add_f32 v[52:53], v[52:53], v[54:55]
	v_pk_fma_f32 v[50:51], v[12:13], v[12:13], v[0:1] op_sel_hi:[1,1,0]
	v_mul_f32_e32 v0, v15, v15
	v_pk_add_f32 v[48:49], v[52:53], v[48:49]
	v_pk_fma_f32 v[52:53], v[14:15], v[14:15], v[0:1] op_sel_hi:[1,1,0]
	v_permlane32_swap_b32_e32 v80, v99
	v_pk_add_f32 v[50:51], v[50:51], v[52:53]
	v_pk_mul_f32 v[52:53], v[62:63], v[100:101] op_sel_hi:[1,0]
	v_pk_add_f32 v[50:51], v[50:51], v[48:49]
	v_cvt_pk_bf16_f32 v48, v12, v13
	v_cvt_pk_bf16_f32 v49, v14, v15
	v_lshlrev_b32_e32 v12, 16, v108
	v_and_b32_e32 v13, 0xffff0000, v108
	v_pk_mul_f32 v[14:15], v[60:61], v[100:101] op_sel_hi:[1,0]
	v_permlane32_swap_b32_e32 v81, v98
	v_pk_mul_f32 v[14:15], v[14:15], v[12:13]
	v_lshlrev_b32_e32 v12, 16, v109
	v_and_b32_e32 v13, 0xffff0000, v109
	v_pk_mul_f32 v[52:53], v[52:53], v[12:13]
	v_mul_f32_e32 v0, v15, v15
	v_pk_fma_f32 v[12:13], v[14:15], v[14:15], v[0:1] op_sel_hi:[1,1,0]
	v_mul_f32_e32 v0, v53, v53
	v_pk_fma_f32 v[54:55], v[52:53], v[52:53], v[0:1] op_sel_hi:[1,1,0]
	v_permlane32_swap_b32_e32 v10, v95
	v_pk_add_f32 v[12:13], v[12:13], v[54:55]
	v_permlane32_swap_b32_e32 v11, v94
	v_pk_add_f32 v[12:13], v[12:13], v[50:51]
	v_cvt_pk_bf16_f32 v50, v14, v15
	v_cvt_pk_bf16_f32 v51, v52, v53
	v_mov_b32_e32 v0, v12
	v_permlane32_swap_b32_e32 v6, v91
	v_permlane32_swap_b32_e32 v7, v90
	v_permlane32_swap_b32_e32 v2, v83
	v_permlane32_swap_b32_e32 v3, v82
	v_permlane32_swap_b32_e32 v48, v50
	v_permlane32_swap_b32_e32 v49, v51
	v_permlane32_swap_b32_e32 v12, v0
	global_store_dwordx4 v[8:9], v[48:51], off offset:96
	s_and_saveexec_b64 s[28:29], s[2:3]
	s_cbranch_execz .LBB0_674
	v_add_f32_e32 v0, v12, v0
	global_store_dword v[4:5], v0, off
